# attention KV loop rewrite + peer_u DPP butterfly + skip the grid barrier after the last layer; compute-dtype comment added
# speedup vs baseline: 1.0168x; 1.0070x over previous
;   DI u16* hb() const { return (u16*)(ws + OFF_hb); }
;   DI u16* yb() const { return (u16*)(ws + OFF_yb); }
;   DI unsigned* bar() const { return (unsigned*)(ws + OFF_bar); }
; #define tid_opaque() tid_from(WAVE_S)
; DI void xcd_barrier(const XcdBarrier& b, const int WAVE_S) {
;   asm volatile("s_waitcnt vmcnt(0)" ::: "memory");
;   __syncthreads();
;   if (tid_opaque() == 0) {
;     unsigned* bar = b.bar;
;     __builtin_amdgcn_s_waitcnt(0);
;     unsigned nloc = b.st[0], nx = b.st[1];
;     if (nloc == 0u) { xcd_barrier_complete(bar, b.x, nloc, nx); b.st[0] = nloc; b.st[1] = nx; }
; __global__ void __launch_bounds__(256, 3) mega_kernel(Params p) {
;     ...
;     ln_rows<1, false, true>(p.yb(), p.hb(), layer == NLAYER - 1 ? nullptr : p.hb(), nullptr, nullptr, layer == NLAYER - 1 ? p.out : nullptr, p.ln2_g + layer * DM, p.ln2_b + layer * DM, T_TOK, WAVE_S);
;     xcd_barrier(xb, WAVE_S);
.LBB0_646:
	s_or_b64 exec, exec, s[34:35]
	v_readlane_b32 s100, v166, 63
	s_cmp_lg_u32 s100, 0
	s_cbranch_scc1 .LBB0_697
	s_waitcnt vmcnt(0)
	s_barrier
	v_mbcnt_lo_u32_b32 v0, -1, 0
	v_mbcnt_hi_u32_b32 v0, -1, v0
	s_nop 0
	v_cmp_eq_u32_e32 vcc, s80, v0
	s_and_saveexec_b64 s[34:35], vcc
	s_cbranch_execz .LBB0_64
	s_waitcnt vmcnt(0) expcnt(0) lgkmcnt(0)
	ds_read_b32 v3, v1 offset:40960
	ds_read_b32 v2, v1 offset:40964
	s_waitcnt lgkmcnt(1)
	v_cmp_ne_u32_e32 vcc, 0, v3
	s_cbranch_vccnz .LBB0_662
	s_mov_b32 s28, 1
	s_branch .LBB0_650

; __global__ void __launch_bounds__(256, 3) mega_kernel(Params p) {
;   __shared__ __attribute__((aligned(16))) char lds[40960];
;   __shared__ uint4 xb_words;
;   cg::grid_group grid = cg::this_grid();
;   const int WAVE_S = __builtin_amdgcn_readfirstlane((int)(threadIdx.x >> 6));
	.amdhsa_kernel _Z11mega_kernel6Params
		.amdhsa_group_segment_fixed_size 40980
		.amdhsa_private_segment_fixed_size 0
		.amdhsa_kernarg_size 416
		.amdhsa_user_sgpr_count 2
		.amdhsa_user_sgpr_dispatch_ptr 0
		.amdhsa_user_sgpr_queue_ptr 0
		.amdhsa_user_sgpr_kernarg_segment_ptr 1
		.amdhsa_user_sgpr_dispatch_id 0
		.amdhsa_user_sgpr_kernarg_preload_length 0
		.amdhsa_user_sgpr_kernarg_preload_offset 0
		.amdhsa_user_sgpr_private_segment_size 0
		.amdhsa_uses_dynamic_stack 0
		.amdhsa_enable_private_segment 0
		.amdhsa_system_sgpr_workgroup_id_x 1
		.amdhsa_system_sgpr_workgroup_id_y 0
		.amdhsa_system_sgpr_workgroup_id_z 0
		.amdhsa_system_sgpr_workgroup_info 0
		.amdhsa_system_vgpr_workitem_id 2
		.amdhsa_next_free_vgpr 168
		.amdhsa_next_free_sgpr 102
		.amdhsa_accum_offset 168
		.amdhsa_reserve_vcc 1
		.amdhsa_float_round_mode_32 0
		.amdhsa_float_round_mode_16_64 0
		.amdhsa_float_denorm_mode_32 3
		.amdhsa_float_denorm_mode_16_64 3
		.amdhsa_dx10_clamp 1
		.amdhsa_ieee_mode 1
		.amdhsa_fp16_overflow 0
		.amdhsa_tg_split 0
		.amdhsa_exception_fp_ieee_invalid_op 0
		.amdhsa_exception_fp_denorm_src 0
		.amdhsa_exception_fp_ieee_div_zero 0
		.amdhsa_exception_fp_ieee_overflow 0
		.amdhsa_exception_fp_ieee_underflow 0
		.amdhsa_exception_fp_ieee_inexact 0
		.amdhsa_exception_int_div_zero 0
	.end_amdhsa_kernel

; __global__ void __launch_bounds__(256, 3) mega_kernel(Params p) {
;   __shared__ __attribute__((aligned(16))) char lds[40960];
;   __shared__ uint4 xb_words;
;   cg::grid_group grid = cg::this_grid();
;   const int WAVE_S = __builtin_amdgcn_readfirstlane((int)(threadIdx.x >> 6));
amdhsa.kernels:
  - .agpr_count:     0
    .args:
      - .offset:         0
        .size:           160
        .value_kind:     by_value
      - .offset:         160
        .size:           4
        .value_kind:     hidden_block_count_x
      - .offset:         164
        .size:           4
        .value_kind:     hidden_block_count_y
      - .offset:         168
        .size:           4
        .value_kind:     hidden_block_count_z
      - .offset:         172
        .size:           2
        .value_kind:     hidden_group_size_x
      - .offset:         174
        .size:           2
        .value_kind:     hidden_group_size_y
      - .offset:         176
        .size:           2
        .value_kind:     hidden_group_size_z
      - .offset:         178
        .size:           2
        .value_kind:     hidden_remainder_x
      - .offset:         180
        .size:           2
        .value_kind:     hidden_remainder_y
      - .offset:         182
        .size:           2
        .value_kind:     hidden_remainder_z
      - .offset:         200
        .size:           8
        .value_kind:     hidden_global_offset_x
      - .offset:         208
        .size:           8
        .value_kind:     hidden_global_offset_y
      - .offset:         216
        .size:           8
        .value_kind:     hidden_global_offset_z
      - .offset:         224
        .size:           2
        .value_kind:     hidden_grid_dims
      - .offset:         248
        .size:           8
        .value_kind:     hidden_multigrid_sync_arg
    .group_segment_fixed_size: 40980
    .kernarg_segment_align: 8
    .kernarg_segment_size: 416
    .language:       OpenCL C
    .language_version:
      - 2
      - 0
    .max_flat_workgroup_size: 256
    .name:           _Z11mega_kernel6Params
    .private_segment_fixed_size: 0
    .sgpr_count:     108
    .sgpr_spill_count: 205
    .symbol:         _Z11mega_kernel6Params.kd
    .uniform_work_group_size: 1
    .uses_dynamic_stack: false
    .vgpr_count:     168
    .vgpr_spill_count: 0
    .wavefront_size: 64
